# diff-attention block A: per-step K/V DMA staging scalar code spread across all PV MFMA gaps (inline fast path when the full batch is staged; original block kept for the last steps)
# speedup vs baseline: 1.0041x; 1.0041x over previous
.LBB0_508:
.LBB0_509:
	s_add_i32 s22, s76, 4
	s_cmp_ge_u32 s22, s19
	s_cbranch_scc1 .LblkA_slow
	s_mov_b32 s32, m0
	s_add_i32 s20, s2, 0xffffc000
	s_and_b32 s20, s20, 0xc000
	v_add_u32_e32 v238, s20, v234
	s_add_i32 s20, s65, s20
	v_mfma_f32_32x32x16_bf16 v[0:15], v[160:163], v[128:131], v[0:15]
	ds_read_b64_tr_b16 v[196:197], v238
	ds_read_b64_tr_b16 v[198:199], v238 offset:512
	v_add_u32_e32 v96, s20, v228
	v_add_u32_e32 v97, s20, v229
	v_add_u32_e32 v98, s20, v230
	v_add_u32_e32 v99, s20, v231
	v_exp_f32_e32 v241, v80
	v_exp_f32_e32 v242, v81
	v_mfma_f32_32x32x16_bf16 v[0:15], v[164:167], v[132:135], v[0:15]
	ds_read_b64_tr_b16 v[192:193], v238 offset:1024
	ds_read_b64_tr_b16 v[194:195], v238 offset:1536
	v_exp_f32_e32 v243, v82
	v_exp_f32_e32 v244, v83
	s_add_i32 s22, s76, 4
	s_and_b64 s[38:39], s[16:17], exec
	s_cselect_b32 s22, s22, s3
	s_ashr_i32 s23, s22, 31
	s_lshl_b64 s[22:23], s[22:23], 16
	s_add_u32 s22, s74, s22
	s_addc_u32 s23, s75, s23
	v_mfma_f32_32x32x16_bf16 v[32:47], v[160:163], v[136:139], v[32:47]
	ds_read_b64_tr_b16 v[188:189], v238 offset:4096
	ds_read_b64_tr_b16 v[190:191], v238 offset:4608
	v_exp_f32_e32 v245, v84
	v_exp_f32_e32 v246, v85
	v_add_f32_e32 v100, v243, v241
	v_add_f32_e32 v101, v244, v242
	s_add_i32 s38, s2, 0x8000
	s_and_b32 s38, s38, 0xc000
	s_add_i32 s38, s54, s38
	s_mov_b32 m0, s38
	s_nop 0
	global_load_lds_dwordx4 v204, s[22:23]
	v_mfma_f32_32x32x16_bf16 v[32:47], v[164:167], v[140:143], v[32:47]
	ds_read_b64_tr_b16 v[184:185], v238 offset:5120
	ds_read_b64_tr_b16 v[186:187], v238 offset:5632
	v_exp_f32_e32 v247, v86
	v_exp_f32_e32 v248, v87
	v_add_f32_e32 v100, v245, v100
	v_add_f32_e32 v101, v246, v101
	s_add_u32 s22, s22, 0x80
	s_addc_u32 s23, s23, 0
	s_addk_i32 s38, 0x2000
	s_mov_b32 m0, s38
	s_nop 0
	global_load_lds_dwordx4 v204, s[22:23]
	v_mfma_f32_32x32x16_bf16 v[48:63], v[160:163], v[144:147], v[48:63]
	ds_read_b64_tr_b16 v[180:181], v238 offset:8192
	ds_read_b64_tr_b16 v[182:183], v238 offset:8704
	v_exp_f32_e32 v249, v88
	v_exp_f32_e32 v250, v89
	v_add_f32_e32 v100, v247, v100
	v_add_f32_e32 v101, v248, v101
	s_add_i32 s22, s76, 3
	s_add_i32 s23, s3, 1
	s_and_b64 s[20:21], s[16:17], exec
	s_cselect_b32 s20, s22, s23
	s_ashr_i32 s21, s20, 31
	s_lshl_b64 s[20:21], s[20:21], 16
	v_mfma_f32_32x32x16_bf16 v[48:63], v[164:167], v[148:151], v[48:63]
	ds_read_b64_tr_b16 v[176:177], v238 offset:9216
	ds_read_b64_tr_b16 v[178:179], v238 offset:9728
	s_add_u32 s20, s80, s20
	s_addc_u32 s21, s81, s21
	s_add_i32 s22, s2, 0x4000
	s_and_b32 s22, s22, 0xc000
	s_add_i32 s22, s22, 0
	s_add_i32 s22, s22, 0x10000
	ds_read_b128 v[128:131], v96 offset:4096
	v_exp_f32_e32 v251, v90
	v_exp_f32_e32 v252, v91
	v_add_f32_e32 v100, v249, v100
	v_add_f32_e32 v101, v250, v101
	v_mfma_f32_32x32x16_bf16 v[16:31], v[160:163], v[152:155], v[16:31]
	ds_read_b64_tr_b16 v[172:173], v238 offset:12288
	ds_read_b64_tr_b16 v[174:175], v238 offset:12800
	v_exp_f32_e32 v253, v92
	v_exp_f32_e32 v239, v93
	v_add_f32_e32 v100, v251, v100
	v_add_f32_e32 v101, v252, v101
	s_add_i32 s23, s22, s55
	s_mov_b32 m0, s23
	s_nop 0
	global_load_lds_dwordx4 v226, s[20:21]
	s_add_i32 s22, s22, s57
	s_mov_b32 m0, s22
	s_nop 0
	global_load_lds_dwordx4 v227, s[20:21]
	v_mfma_f32_32x32x16_bf16 v[16:31], v[164:167], v[156:159], v[16:31]
	ds_read_b64_tr_b16 v[168:169], v238 offset:13312
	ds_read_b64_tr_b16 v[170:171], v238 offset:13824
	ds_read_b128 v[132:135], v97 offset:4096
	ds_read_b128 v[136:139], v98 offset:4096
	ds_read_b128 v[140:143], v99 offset:4096
	v_exp_f32_e32 v240, v94
	v_exp_f32_e32 v99, v95
	v_add_f32_e32 v100, v253, v100
	v_add_f32_e32 v101, v239, v101
	v_add_f32_e32 v100, v240, v100
	v_add_f32_e32 v101, v99, v101
	v_add_f32_e32 v100, v100, v101
	v_add_f32_e32 v235, v235, v100
	v_cvt_pk_bf16_f32 v156, v241, v242
	v_cvt_pk_bf16_f32 v157, v243, v244
	v_cvt_pk_bf16_f32 v158, v245, v246
	v_cvt_pk_bf16_f32 v159, v247, v248
	v_cvt_pk_bf16_f32 v162, v249, v250
	v_cvt_pk_bf16_f32 v163, v251, v252
	v_cvt_pk_bf16_f32 v164, v253, v239
	v_cvt_pk_bf16_f32 v165, v240, v99
	s_waitcnt lgkmcnt(7)
	v_mfma_f32_32x32x16_bf16 v[96:111], v[128:131], v[112:115], v[64:79]
	v_max3_f32 v144, v80, v81, v82
	v_max3_f32 v145, v83, v84, v85
	s_waitcnt lgkmcnt(2)
	v_mfma_f32_32x32x16_bf16 v[96:111], v[132:135], v[116:119], v[96:111]
	v_max3_f32 v128, v144, v86, v87
	v_max3_f32 v129, v145, v88, v89
	s_waitcnt lgkmcnt(1)
	v_mfma_f32_32x32x16_bf16 v[96:111], v[136:139], v[120:123], v[96:111]
	v_max3_f32 v128, v128, v90, v91
	v_max3_f32 v129, v129, v92, v93
	s_nop 0
	v_max3_f32 v128, v128, v94, v95
	s_waitcnt lgkmcnt(0)
	v_mfma_f32_32x32x16_bf16 v[96:111], v[140:143], v[124:127], v[96:111]
	v_max_f32_e32 v128, v128, v129
	ds_bpermute_b32 v129, v214, v128
	s_mov_b32 m0, s32
	s_andn2_b64 vcc, exec, s[0:1]
	s_cbranch_vccz .LBB0_522

.LblkA_slow:
	s_add_i32 s20, s2, 0xffffc000
	s_and_b32 s20, s20, 0xc000
	v_add_u32_e32 v238, s20, v234
	s_add_i32 s20, s65, s20
	v_mfma_f32_32x32x16_bf16 v[0:15], v[160:163], v[128:131], v[0:15]
	ds_read_b64_tr_b16 v[196:197], v238
	ds_read_b64_tr_b16 v[198:199], v238 offset:512
	v_add_u32_e32 v96, s20, v228
	v_add_u32_e32 v97, s20, v229
	v_add_u32_e32 v98, s20, v230
	v_add_u32_e32 v99, s20, v231
	v_exp_f32_e32 v241, v80
	v_exp_f32_e32 v242, v81
	v_mfma_f32_32x32x16_bf16 v[0:15], v[164:167], v[132:135], v[0:15]
	ds_read_b64_tr_b16 v[192:193], v238 offset:1024
	ds_read_b64_tr_b16 v[194:195], v238 offset:1536
	v_exp_f32_e32 v243, v82
	v_exp_f32_e32 v244, v83
	s_add_i32 s22, s76, 4
	s_cmp_ge_u32 s22, s19
	s_cbranch_scc1 .LstgK_skip
	s_and_b64 s[38:39], s[16:17], exec
	s_cselect_b32 s22, s22, s3
	s_ashr_i32 s23, s22, 31
	s_lshl_b64 s[22:23], s[22:23], 16
	s_add_u32 s22, s74, s22
	s_addc_u32 s23, s75, s23
	s_add_i32 s38, s2, 0x8000
	s_and_b32 s38, s38, 0xc000
	s_add_i32 s38, s54, s38
	s_mov_b32 s39, m0
	s_mov_b32 m0, s38
	s_nop 0
	global_load_lds_dwordx4 v204, s[22:23]
	s_mov_b32 m0, s39
	s_add_u32 s22, s22, 0x80
	s_addc_u32 s23, s23, 0
	s_addk_i32 s38, 0x2000
	s_mov_b32 s39, m0
	s_mov_b32 m0, s38
	s_nop 0
	global_load_lds_dwordx4 v204, s[22:23]
	s_mov_b32 m0, s39

.LstgV_skip:
	v_mfma_f32_32x32x16_bf16 v[48:63], v[160:163], v[144:147], v[48:63]
	ds_read_b64_tr_b16 v[180:181], v238 offset:8192
	ds_read_b64_tr_b16 v[182:183], v238 offset:8704
	v_exp_f32_e32 v249, v88
	v_exp_f32_e32 v250, v89
	v_add_f32_e32 v100, v247, v100
	v_add_f32_e32 v101, v248, v101
	v_mfma_f32_32x32x16_bf16 v[48:63], v[164:167], v[148:151], v[48:63]
	ds_read_b64_tr_b16 v[176:177], v238 offset:9216
	ds_read_b64_tr_b16 v[178:179], v238 offset:9728
	ds_read_b128 v[128:131], v96 offset:4096
	v_exp_f32_e32 v251, v90
	v_exp_f32_e32 v252, v91
	v_add_f32_e32 v100, v249, v100
	v_add_f32_e32 v101, v250, v101
	v_mfma_f32_32x32x16_bf16 v[16:31], v[160:163], v[152:155], v[16:31]
	ds_read_b64_tr_b16 v[172:173], v238 offset:12288
	ds_read_b64_tr_b16 v[174:175], v238 offset:12800
	v_exp_f32_e32 v253, v92
	v_exp_f32_e32 v239, v93
	v_add_f32_e32 v100, v251, v100
	v_add_f32_e32 v101, v252, v101
	v_mfma_f32_32x32x16_bf16 v[16:31], v[164:167], v[156:159], v[16:31]
	ds_read_b64_tr_b16 v[168:169], v238 offset:13312
	ds_read_b64_tr_b16 v[170:171], v238 offset:13824
	ds_read_b128 v[132:135], v97 offset:4096
	ds_read_b128 v[136:139], v98 offset:4096
	ds_read_b128 v[140:143], v99 offset:4096
	v_exp_f32_e32 v240, v94
	v_exp_f32_e32 v99, v95
	v_add_f32_e32 v100, v253, v100
	v_add_f32_e32 v101, v239, v101
	v_add_f32_e32 v100, v240, v100
	v_add_f32_e32 v101, v99, v101
	v_add_f32_e32 v100, v100, v101
	v_add_f32_e32 v235, v235, v100
	v_cvt_pk_bf16_f32 v156, v241, v242
	v_cvt_pk_bf16_f32 v157, v243, v244
	v_cvt_pk_bf16_f32 v158, v245, v246
	v_cvt_pk_bf16_f32 v159, v247, v248
	v_cvt_pk_bf16_f32 v162, v249, v250
	v_cvt_pk_bf16_f32 v163, v251, v252
	v_cvt_pk_bf16_f32 v164, v253, v239
	v_cvt_pk_bf16_f32 v165, v240, v99
	s_waitcnt lgkmcnt(7)
	v_mfma_f32_32x32x16_bf16 v[96:111], v[128:131], v[112:115], v[64:79]
	v_max3_f32 v144, v80, v81, v82
	v_max3_f32 v145, v83, v84, v85
	s_waitcnt lgkmcnt(2)
	v_mfma_f32_32x32x16_bf16 v[96:111], v[132:135], v[116:119], v[96:111]
	v_max3_f32 v128, v144, v86, v87
	v_max3_f32 v129, v145, v88, v89
	s_waitcnt lgkmcnt(1)
	v_mfma_f32_32x32x16_bf16 v[96:111], v[136:139], v[120:123], v[96:111]
	v_max3_f32 v128, v128, v90, v91
	v_max3_f32 v129, v129, v92, v93
	s_nop 0
	v_max3_f32 v128, v128, v94, v95
	s_waitcnt lgkmcnt(0)
	v_mfma_f32_32x32x16_bf16 v[96:111], v[140:143], v[124:127], v[96:111]
	v_max_f32_e32 v128, v128, v129
	ds_bpermute_b32 v129, v214, v128
	s_andn2_b64 vcc, exec, s[0:1]
	s_cbranch_vccz .LBB0_522
	s_branch .LBB0_510
